# plus: next-layer W_in conversion items moved to waves that had only one item (max 2 items per wave instead of 3)
# speedup vs baseline: 1.0108x; 1.0049x over previous
; __global__ void __launch_bounds__(512, 2) mk_fwd(Args a) {
;     ...
;                 const int gw = (bx - 64) * 8 + wave, NGW = (G - 64) * 8;
;                 constexpr int I_GLU = (512 / 64) * (1024 / 64), I_OUT = (DM / 64) * (DM / 64), I_1 = (DM / 64) * (FF / 64), I_2 = (FF / 64) * (DM / 64);
;                 for (int it = gw; it < I_GLU + I_OUT + I_1 + I_2; it += NGW) {
;                     int r = it;
;                     if (r < I_GLU) { p0_transpose_item<1>(a.w_glu + (size_t)layer * 512 * 1024, 512, 1024, nullptr, WGLU, scr, r, lane); continue; } r -= I_GLU;
;                     if (r < I_OUT) { p0_transpose_item<0>(a.w_out + (size_t)layer * DM * DM, DM, DM, nullptr, WOUT, scr, r, lane); continue; } r -= I_OUT;
;                     if (r < I_1) { p0_transpose_item<0>(a.w_ff1 + (size_t)layer * DM * FF, DM, FF, a.norm2 + layer * DM, W1, scr, r, lane); continue; } r -= I_1;
;                     p0_transpose_item<0>(a.w_ff2 + (size_t)layer * FF * DM, FF, DM, nullptr, W2, scr, r, lane);
;                 }
;                 if (layer + 1 < DEPTH) for (int it = gw; it < (DM / 64) * (INW / 64); it += NGW) p0_transpose_item<0>(a.w_in + (size_t)(layer + 1) * DM * INW, DM, INW, a.norm1 + (layer + 1) * DM, WINN, scr, it, lane);
.LBB0_355:
	s_or_b64 exec, exec, s[20:21]
	v_subrev_u32_e32 v69, 0x380, v69
	v_lshlrev_b32_e32 v70, 6, v69
	v_readlane_b32 s8, v255, 41
	s_movk_i32 s5, 0x140
	v_readlane_b32 s9, v255, 42
	v_cmp_gt_u32_e32 vcc, s5, v69
	s_xor_b64 s[8:9], s[8:9], -1
	s_and_b64 s[8:9], s[8:9], vcc
	s_and_saveexec_b64 s[10:11], s[8:9]
	v_readlane_b32 s12, v255, 28
	v_readlane_b32 s14, v255, 30
	v_readlane_b32 s13, v255, 29
	v_readlane_b32 s15, v255, 31
	s_cbranch_execz .LBB0_358
	s_and_b64 s[8:9], s[64:65], exec
	s_cselect_b32 s5, 0xfc00000, s6
	s_add_u32 s12, s92, s5
	s_mul_i32 s8, s52, 0x140000
	s_mov_b32 s9, s59
	v_readlane_b32 s64, v253, 9
	s_addc_u32 s5, s93, 0
	s_lshl_b64 s[8:9], s[8:9], 2
	v_readlane_b32 s68, v253, 13
	v_readlane_b32 s69, v253, 14
	s_add_u32 s8, s68, s8
	s_addc_u32 s9, s69, s9
	s_lshl_b32 s16, s52, 10
	s_mov_b32 s17, s59
	v_readlane_b32 s66, v253, 11
	s_lshl_b64 s[16:17], s[16:17], 2
	v_lshlrev_b32_e32 v0, 11, v90
	v_and_b32_e32 v1, 7, v184
	v_readlane_b32 s67, v253, 12
	s_add_u32 s16, s66, s16
	v_mov_b32_e32 v73, v201
	v_lshl_or_b32 v0, v69, 17, v0
	v_lshlrev_b32_e32 v1, 4, v1
	s_mov_b32 s1, 0x1c000
	s_addc_u32 s17, s67, s17
	v_lshl_add_u64 v[56:57], s[8:9], 0, v[72:73]
	s_and_b32 s13, s5, 0xffff
	s_mov_b32 s15, s95
	v_or3_b32 v58, v0, v1, s1
	s_lshl_b32 s5, s37, 17
	s_lshl_b32 s7, s37, 6
	s_mov_b64 s[20:21], 0
	v_readlane_b32 s65, v253, 10
	v_readlane_b32 s70, v253, 15
	v_readlane_b32 s71, v253, 16
	v_readlane_b32 s72, v253, 17
	v_readlane_b32 s73, v253, 18
	v_readlane_b32 s74, v253, 19
	v_readlane_b32 s75, v253, 20
	v_readlane_b32 s76, v253, 21
	v_readlane_b32 s77, v253, 22
	v_readlane_b32 s78, v253, 23
	v_readlane_b32 s79, v253, 24
